# static s_setprio 1 for waves 4-7 during M3 (younger-half priority raise)
# baseline (speedup 1.0000x reference)
; __device__ __forceinline__ void m3_phase(const Params& p, unsigned char* ldsg, int G) {
;     const int tid = threadIdx.x, lane = tid & 63, wave = __builtin_amdgcn_readfirstlane(tid >> 6), fr = lane & 15, fq = lane >> 4;
;     unsigned char* ws = p.ws;
;     const bf16* PROJ = (const bf16*)(ws + WS_HB); const float* GATES = (const float*)(ws + WS_GATES); const bf16* QKC = (const bf16*)((const unsigned char*)p.out + 32 * MiB);
;     const bf16* CPB = (const bf16*)p.out; const float* DN = (const float*)(ws + WS_DN); const float* MPREV = (const float*)(ws + WS_SC) + 2048;
;     bf16* MIX = (bf16*)(ws + WS_MIX);
;     bf16* Qs = (bf16*)(ldsg + L_QS); bf16* Ks = (bf16*)(ldsg + L_KS); bf16* VT = (bf16*)(ldsg + L_VT); bf16* CTs = (bf16*)(ldsg + L_CT); bf16* Ps = (bf16*)(ldsg + L_PS); bf16* Os = (bf16*)(ldsg + L_OS);
;     float* sU = (float*)(ldsg + L_SM); float* sM = sU + 64; float* sIW = sU + 128; float* sEMT = sU + 192; float* sRS = sU + 256; float* sQN = sU + 320; float* sHS = sU + 384; float* sN = sU + 448;
;     ...
;     u32x4 gq[2], gk[2], gv[2], go[2], gc[4]; float g_ig = 0.f, g_fp = 0.f, g_mp = 0.f, g_n0 = 0.f, g_n1 = 0.f;
;     ...
;     if ((int)blockIdx.x < NCH * NH) M3_ISSUE((int)blockIdx.x);
.LBB0_1114:
	s_or_b64 exec, exec, s[4:5]
	s_add_u32 s20, s72, 0x480000
	s_addc_u32 s21, s73, 0
	s_cmpk_lt_i32 s86, 0x400
	s_cselect_b64 s[4:5], -1, 0
	s_cmpk_gt_i32 s86, 0x3ff
	v_readfirstlane_b32 s3, v152
	s_waitcnt lgkmcnt(0)
	s_barrier
	s_cbranch_scc1 .LBB0_1116
	s_cmpk_gt_u32 s3, 0xff
	s_cbranch_scc0 .Lm3prio
	s_setprio 1
.Lm3prio:
	s_ashr_i32 s2, s86, 2
	s_lshl_b32 s11, s2, 6
	v_or_b32_e32 v16, s11, v165
	v_ashrrev_i32_e32 v17, 31, v16
	s_and_b32 s10, s86, 3
	v_lshlrev_b64 v[0:1], 11, v[16:17]
	v_lshl_add_u64 v[0:1], s[56:57], 0, v[0:1]
	s_lshl_b32 s6, s10, 8
	s_mov_b32 s7, 0
	v_lshl_add_u64 v[0:1], v[0:1], 0, s[6:7]
	v_and_b32_e32 v50, 0xf0, v247
	v_mov_b32_e32 v51, 0
	v_lshl_add_u64 v[4:5], v[0:1], 0, v[50:51]
	s_movk_i32 s12, 0x1600
	v_mov_b64_e32 v[18:19], s[78:79]
	global_load_dwordx4 v[8:11], v[4:5], off
	global_load_dwordx4 v[0:3], v[4:5], off offset:1024
	v_mad_i64_i32 v[4:5], s[8:9], v16, s12, v[18:19]
	v_add_u32_e32 v16, 32, v16
	v_ashrrev_i32_e32 v17, 31, v16
	v_lshlrev_b64 v[20:21], 11, v[16:17]
	v_lshl_add_u64 v[20:21], s[56:57], 0, v[20:21]
	v_mad_i64_i32 v[16:17], s[8:9], v16, s12, v[18:19]
	v_lshl_add_u64 v[4:5], v[4:5], 0, s[6:7]
	v_lshl_add_u64 v[20:21], v[20:21], 0, s[6:7]
	v_lshl_add_u64 v[16:17], v[16:17], 0, s[6:7]
	s_lshl_b32 s6, s10, 14
	s_add_i32 s2, s6, s2
	v_and_b32_e32 v32, 0x1f00, v230
	v_add_u32_e32 v42, s2, v32
	v_lshl_add_u64 v[12:13], v[4:5], 0, v[50:51]
	v_lshl_add_u64 v[28:29], v[20:21], 0, v[50:51]
	v_ashrrev_i32_e32 v43, 31, v42
	global_load_dwordx4 v[4:7], v[12:13], off offset:2048
	s_nop 0
	global_load_dwordx4 v[12:15], v[12:13], off offset:3072
	s_nop 0
	global_load_dwordx4 v[24:27], v[28:29], off
	global_load_dwordx4 v[20:23], v[28:29], off offset:1024
	v_lshl_add_u64 v[28:29], v[16:17], 0, v[50:51]
	v_and_b32_e32 v50, 0x1f0, v247
	v_lshlrev_b64 v[32:33], 9, v[42:43]
	v_add_u32_e32 v42, 0x2000, v42
	v_lshl_add_u64 v[40:41], s[70:71], 0, v[50:51]
	v_ashrrev_i32_e32 v43, 31, v42
	v_lshl_add_u64 v[44:45], v[40:41], 0, v[32:33]
	v_add_u32_e32 v32, 0x1000, v230
	v_lshlrev_b64 v[42:43], 9, v[42:43]
	v_and_b32_e32 v32, 0x3f00, v32
	v_lshl_add_u64 v[52:53], v[40:41], 0, v[42:43]
	v_add_u32_e32 v42, 0x3000, v230
	v_add_u32_e32 v32, s2, v32
	v_and_b32_e32 v42, 0x7f00, v42
	v_ashrrev_i32_e32 v33, 31, v32
	v_add_u32_e32 v42, s2, v42
	v_lshlrev_b64 v[32:33], 9, v[32:33]
	v_ashrrev_i32_e32 v43, 31, v42
	v_lshl_add_u64 v[46:47], v[40:41], 0, v[32:33]
	v_lshlrev_b64 v[42:43], 9, v[42:43]
	global_load_dwordx4 v[16:19], v[28:29], off offset:2048
	s_nop 0
	global_load_dwordx4 v[28:31], v[28:29], off offset:3072
	s_nop 0
	global_load_dwordx4 v[32:35], v[44:45], off
	global_load_dwordx4 v[36:39], v[46:47], off
	v_lshl_add_u64 v[54:55], v[40:41], 0, v[42:43]
	global_load_dwordx4 v[40:43], v[52:53], off
	global_load_dwordx4 v[44:47], v[54:55], off
	v_or_b32_e32 v52, s11, v153
	v_ashrrev_i32_e32 v53, 31, v52
	v_lshlrev_b64 v[52:53], 5, v[52:53]
	v_lshl_add_u64 v[52:53], s[54:55], 0, v[52:53]
	s_lshl_b32 s6, s10, 2
	s_mulk_i32 s10, 0xc100
	v_lshl_add_u64 v[52:53], v[52:53], 0, s[6:7]
	s_add_i32 s6, s2, s10
	s_ashr_i32 s7, s6, 31
	s_lshl_b64 s[8:9], s[6:7], 2
	s_add_u32 s8, s0, s8
	s_addc_u32 s9, s1, s9
	s_lshl_b64 s[6:7], s[6:7], 9
	s_add_u32 s6, s20, s6
	s_addc_u32 s7, s21, s7
	global_load_dword v130, v[52:53], off
	global_load_dword v193, v[52:53], off offset:16
	global_load_dword v111, v51, s[8:9]
	global_load_dword v195, v48, s[6:7]
	global_load_dword v194, v48, s[6:7] offset:256
	s_add_u32 s48, s72, 0x8800000
	s_addc_u32 s49, s73, 0
	s_andn2_b64 vcc, exec, s[4:5]
	s_cbranch_vccz .LBB0_1117
	s_branch .LBB0_1159

; #define GSYNC() xcd_barrier(xb)
; __device__ __forceinline__ void xcd_barrier(const XcdBarrier& b) {
;     asm volatile("s_waitcnt vmcnt(0)" ::: "memory");
;     __syncthreads();
;     if (threadIdx.x == 0) {
;         unsigned* bar = b.bar;
;         __builtin_amdgcn_s_waitcnt(0);
;         unsigned nloc = b.st[0], nx = b.st[1];
;         if (nloc == 0u) { xcd_barrier_complete(bar, b.x, nloc, nx); b.st[0] = nloc; b.st[1] = nx; }
; __global__ void __launch_bounds__(512, 2) fwd_megakernel(Params p) {
;     ...
;     m3_phase(p, lds, G);
;     GSYNC();
.LBB0_1159:
	s_setprio 0
	s_waitcnt vmcnt(0)
	s_barrier
	s_mov_b64 s[0:1], exec
	v_readlane_b32 s2, v255, 2
	v_readlane_b32 s3, v255, 3
	s_and_b64 s[2:3], s[0:1], s[2:3]
	s_mov_b64 exec, s[2:3]
	s_cbranch_execz .LBB0_1211
	s_add_i32 s2, 0, 0x20000
	s_waitcnt vmcnt(15)
	v_mov_b32_e32 v0, s2
	s_waitcnt vmcnt(0) expcnt(0) lgkmcnt(0)
	ds_read_b32 v2, v0
	s_add_i32 s2, 0, 0x20004
	v_mov_b32_e32 v0, s2
	ds_read_b32 v0, v0
	s_waitcnt lgkmcnt(1)
	v_cmp_ne_u32_e32 vcc, 0, v2
	s_cbranch_vccnz .LBB0_1175
	s_add_u32 s4, s72, 0x580200
	s_addc_u32 s5, s73, 0
	s_add_u32 s6, s72, 0x580400
	s_addc_u32 s7, s73, 0
	s_add_u32 s8, s72, 0x580500
	s_addc_u32 s9, s73, 0
	s_add_u32 s10, s72, 0x580600
	s_addc_u32 s11, s73, 0
	s_add_u32 s12, s72, 0x580700
	s_addc_u32 s13, s73, 0
	s_add_u32 s14, s72, 0x580800
	s_addc_u32 s15, s73, 0
	s_add_u32 s16, s72, 0x580900
	s_addc_u32 s17, s73, 0
	s_add_u32 s18, s72, 0x580a00
	s_addc_u32 s19, s73, 0
	s_add_u32 s20, s72, 0x580b00
	s_addc_u32 s21, s73, 0
	s_add_u32 s22, s72, 0x580c00
	s_addc_u32 s23, s73, 0
	s_add_u32 s24, s72, 0x580d00
	s_addc_u32 s25, s73, 0
	s_add_u32 s26, s72, 0x580e00
	s_addc_u32 s27, s73, 0
	s_add_u32 s28, s72, 0x580f00
	s_addc_u32 s29, s73, 0
	s_add_u32 s30, s72, 0x581000
	s_addc_u32 s31, s73, 0
	s_add_u32 s34, s72, 0x581100
	s_addc_u32 s35, s73, 0
	s_add_u32 s36, s72, 0x581200
	v_readlane_b32 s2, v255, 0
	s_addc_u32 s37, s73, 0
	s_mul_i32 s2, s75, s2
	s_add_u32 s38, s72, 0x581300
	s_mul_i32 s2, s2, s74
	s_addc_u32 s39, s73, 0
	s_mov_b32 s3, 1
	v_mov_b32_e32 v16, 0
	s_branch .LBB0_1163
